# last-layer epilogue pass 1: residual loads issued two rows ahead into rotating register buffers instead of 16 serialized round trips
# baseline (speedup 1.0000x reference)
.LBB0_790:
	v_and_b32_e32 v139, 64, v227
	v_xor_b32_e32 v138, 16, v227
	v_add_u32_e32 v139, 64, v139
	v_cmp_lt_i32_e32 vcc, v138, v139
	v_lshl_add_u32 v152, s44, 8, v168
	v_ashrrev_i32_e32 v153, 31, v152
	v_cndmask_b32_e32 v138, v227, v138, vcc
	v_lshlrev_b32_e32 v172, 2, v138
	v_xor_b32_e32 v138, 32, v227
	v_cmp_lt_i32_e32 vcc, v138, v139
	v_lshl_or_b32 v140, s20, 8, v170
	v_ashrrev_i32_e32 v141, 31, v140
	v_cndmask_b32_e32 v138, v227, v138, vcc
	v_lshlrev_b32_e32 v173, 2, v138
	v_lshlrev_b64 v[138:139], 12, v[152:153]
	v_lshl_add_u64 v[138:139], s[22:23], 0, v[138:139]
	v_lshl_add_u64 v[138:139], v[140:141], 2, v[138:139]
	global_load_dwordx4 v[128:131], v[138:139], off offset:16 nt
	global_load_dwordx4 v[132:135], v[138:139], off nt
	global_load_dwordx4 v[202:205], v[138:139], off offset:528 nt
	global_load_dwordx4 v[206:209], v[138:139], off offset:512 nt
	s_mov_b64 s[100:101], 0x10000
	v_lshl_add_u64 v[250:251], v[138:139], 0, s[100:101]
	global_load_dwordx4 v[210:213], v[250:251], off offset:16 nt
	global_load_dwordx4 v[214:217], v[250:251], off nt
	global_load_dwordx4 v[218:221], v[250:251], off offset:528 nt
	global_load_dwordx4 v[230:233], v[250:251], off offset:512 nt
	s_mov_b64 s[100:101], 0x20000
	v_lshl_add_u64 v[250:251], v[138:139], 0, s[100:101]
	global_load_dwordx4 v[234:237], v[250:251], off offset:16 nt
	global_load_dwordx4 v[238:241], v[250:251], off nt
	global_load_dwordx4 v[242:245], v[250:251], off offset:528 nt
	global_load_dwordx4 v[246:249], v[250:251], off offset:512 nt
	s_waitcnt vmcnt(8)
	v_mov_b64_e32 v[142:143], v[128:129]
	v_mov_b64_e32 v[144:145], v[130:131]
	v_mov_b64_e32 v[146:147], v[132:133]
	v_mov_b64_e32 v[148:149], v[134:135]
	v_pk_add_f32 v[122:123], v[122:123], v[144:145]
	v_pk_add_f32 v[126:127], v[126:127], v[148:149]
	v_pk_add_f32 v[124:125], v[124:125], v[146:147]
	v_mov_b64_e32 v[146:147], v[202:203]
	v_mov_b64_e32 v[148:149], v[204:205]
	v_mov_b64_e32 v[154:155], v[206:207]
	v_mov_b64_e32 v[156:157], v[208:209]
	v_pk_add_f32 v[120:121], v[120:121], v[142:143]
	v_mul_f32_e32 v150, v125, v125
	v_fmac_f32_e32 v150, v124, v124
	v_fmac_f32_e32 v150, v126, v126
	v_fmac_f32_e32 v150, v127, v127
	v_fmac_f32_e32 v150, v120, v120
	v_fmac_f32_e32 v150, v121, v121
	v_fmac_f32_e32 v150, v122, v122
	v_fmac_f32_e32 v150, v123, v123
	v_pk_add_f32 v[144:145], v[116:117], v[154:155]
	v_pk_add_f32 v[142:143], v[118:119], v[156:157]
	v_pk_add_f32 v[118:119], v[112:113], v[146:147]
	v_mul_f32_e32 v112, v145, v145
	v_fmac_f32_e32 v112, v144, v144
	v_fmac_f32_e32 v112, v142, v142
	v_fmac_f32_e32 v112, v143, v143
	v_fmac_f32_e32 v112, v118, v118
	v_pk_add_f32 v[116:117], v[114:115], v[148:149]
	v_fmac_f32_e32 v112, v119, v119
	v_fmac_f32_e32 v112, v116, v116
	v_fmac_f32_e32 v112, v117, v117
	v_add_f32_e32 v112, v150, v112
	ds_bpermute_b32 v113, v172, v112
	s_waitcnt lgkmcnt(0)
	v_add_f32_e32 v114, v112, v113
	ds_bpermute_b32 v115, v173, v114
	v_lshl_add_u64 v[112:113], v[152:153], 2, s[12:13]
	s_and_saveexec_b64 s[34:35], s[38:39]
	s_mov_b32 s67, 0xa000
	s_movk_i32 s73, 0x3000
	s_cbranch_execz .LBB0_792
	s_waitcnt lgkmcnt(0)
	v_add_f32_e32 v114, v114, v115
	global_atomic_add_f32 v[112:113], v114, off
.LBB0_792:
	s_or_b64 exec, exec, s[34:35]
	v_or_b32_e32 v158, 16, v152
	v_ashrrev_i32_e32 v159, 31, v158
	s_waitcnt lgkmcnt(0)
	v_lshlrev_b64 v[114:115], 12, v[158:159]
	v_lshl_add_u64 v[114:115], s[22:23], 0, v[114:115]
	v_lshl_add_u64 v[114:115], v[140:141], 2, v[114:115]
	s_mov_b64 s[100:101], 0x30000
	v_lshl_add_u64 v[250:251], v[138:139], 0, s[100:101]
	global_load_dwordx4 v[128:131], v[250:251], off offset:16 nt
	global_load_dwordx4 v[132:135], v[250:251], off nt
	global_load_dwordx4 v[202:205], v[250:251], off offset:528 nt
	global_load_dwordx4 v[206:209], v[250:251], off offset:512 nt
	s_waitcnt vmcnt(8)
	v_mov_b64_e32 v[146:147], v[210:211]
	v_mov_b64_e32 v[148:149], v[212:213]
	v_mov_b64_e32 v[154:155], v[214:215]
	v_mov_b64_e32 v[156:157], v[216:217]
	v_pk_add_f32 v[106:107], v[106:107], v[148:149]
	v_pk_add_f32 v[110:111], v[110:111], v[156:157]
	v_pk_add_f32 v[108:109], v[108:109], v[154:155]
	v_mov_b64_e32 v[148:149], v[218:219]
	v_mov_b64_e32 v[150:151], v[220:221]
	v_mov_b64_e32 v[154:155], v[230:231]
	v_mov_b64_e32 v[156:157], v[232:233]
	v_pk_add_f32 v[104:105], v[104:105], v[146:147]
	v_mul_f32_e32 v153, v109, v109
	v_fmac_f32_e32 v153, v108, v108
	v_fmac_f32_e32 v153, v110, v110
	v_fmac_f32_e32 v153, v111, v111
	v_fmac_f32_e32 v153, v104, v104
	v_fmac_f32_e32 v153, v105, v105
	v_fmac_f32_e32 v153, v106, v106
	v_fmac_f32_e32 v153, v107, v107
	v_pk_add_f32 v[98:99], v[98:99], v[150:151]
	v_pk_add_f32 v[146:147], v[100:101], v[154:155]
	v_pk_add_f32 v[100:101], v[96:97], v[148:149]
	v_mul_f32_e32 v96, v147, v147
	v_pk_add_f32 v[102:103], v[102:103], v[156:157]
	v_fmac_f32_e32 v96, v146, v146
	v_fmac_f32_e32 v96, v102, v102
	v_fmac_f32_e32 v96, v103, v103
	v_fmac_f32_e32 v96, v100, v100
	v_fmac_f32_e32 v96, v101, v101
	v_fmac_f32_e32 v96, v98, v98
	v_fmac_f32_e32 v96, v99, v99
	v_add_f32_e32 v96, v153, v96
	ds_bpermute_b32 v97, v172, v96
	v_lshl_add_u64 v[148:149], v[158:159], 2, s[12:13]
	s_waitcnt lgkmcnt(0)
	v_add_f32_e32 v96, v96, v97
	ds_bpermute_b32 v97, v173, v96
	s_and_saveexec_b64 s[34:35], s[38:39]
	s_cbranch_execz .LBB0_794
	s_waitcnt lgkmcnt(0)
	v_add_f32_e32 v96, v96, v97
	global_atomic_add_f32 v[148:149], v96, off
.LBB0_794:
	s_or_b64 exec, exec, s[34:35]
	v_or_b32_e32 v162, 32, v152
	v_ashrrev_i32_e32 v163, 31, v162
	s_waitcnt lgkmcnt(0)
	v_lshlrev_b64 v[96:97], 12, v[162:163]
	v_lshl_add_u64 v[96:97], s[22:23], 0, v[96:97]
	v_lshl_add_u64 v[96:97], v[140:141], 2, v[96:97]
	s_mov_b64 s[100:101], 0x80000
	v_lshl_add_u64 v[250:251], v[138:139], 0, s[100:101]
	global_load_dwordx4 v[210:213], v[250:251], off offset:16 nt
	global_load_dwordx4 v[214:217], v[250:251], off nt
	global_load_dwordx4 v[218:221], v[250:251], off offset:528 nt
	global_load_dwordx4 v[230:233], v[250:251], off offset:512 nt
	s_waitcnt vmcnt(8)
	v_mov_b64_e32 v[154:155], v[234:235]
	v_mov_b64_e32 v[156:157], v[236:237]
	v_mov_b64_e32 v[158:159], v[238:239]
	v_mov_b64_e32 v[160:161], v[240:241]
	v_pk_add_f32 v[90:91], v[90:91], v[156:157]
	v_pk_add_f32 v[94:95], v[94:95], v[160:161]
	v_pk_add_f32 v[92:93], v[92:93], v[158:159]
	v_pk_add_f32 v[88:89], v[88:89], v[154:155]
	v_mov_b64_e32 v[154:155], v[242:243]
	v_mov_b64_e32 v[156:157], v[244:245]
	v_mov_b64_e32 v[158:159], v[246:247]
	v_mov_b64_e32 v[160:161], v[248:249]
	v_mul_f32_e32 v153, v93, v93
	v_fmac_f32_e32 v153, v92, v92
	v_fmac_f32_e32 v153, v94, v94
	v_fmac_f32_e32 v153, v95, v95
	v_fmac_f32_e32 v153, v88, v88
	v_fmac_f32_e32 v153, v89, v89
	v_fmac_f32_e32 v153, v90, v90
	v_fmac_f32_e32 v153, v91, v91
	v_pk_add_f32 v[82:83], v[82:83], v[156:157]
	v_pk_add_f32 v[150:151], v[84:85], v[158:159]
	v_pk_add_f32 v[84:85], v[80:81], v[154:155]
	v_mul_f32_e32 v80, v151, v151
	v_pk_add_f32 v[86:87], v[86:87], v[160:161]
	v_fmac_f32_e32 v80, v150, v150
	v_fmac_f32_e32 v80, v86, v86
	v_fmac_f32_e32 v80, v87, v87
	v_fmac_f32_e32 v80, v84, v84
	v_fmac_f32_e32 v80, v85, v85
	v_fmac_f32_e32 v80, v82, v82
	v_fmac_f32_e32 v80, v83, v83
	v_add_f32_e32 v80, v153, v80
	ds_bpermute_b32 v81, v172, v80
	v_lshl_add_u64 v[154:155], v[162:163], 2, s[12:13]
	s_waitcnt lgkmcnt(0)
	v_add_f32_e32 v80, v80, v81
	ds_bpermute_b32 v81, v173, v80
	s_and_saveexec_b64 s[34:35], s[38:39]
	s_cbranch_execz .LBB0_796
	s_waitcnt lgkmcnt(0)
	v_add_f32_e32 v80, v80, v81
	global_atomic_add_f32 v[154:155], v80, off
.LBB0_796:
	s_or_b64 exec, exec, s[34:35]
	v_or_b32_e32 v166, 48, v152
	v_ashrrev_i32_e32 v167, 31, v166
	s_waitcnt lgkmcnt(0)
	v_lshlrev_b64 v[80:81], 12, v[166:167]
	v_lshl_add_u64 v[80:81], s[22:23], 0, v[80:81]
	v_lshl_add_u64 v[80:81], v[140:141], 2, v[80:81]
	s_mov_b64 s[100:101], 0x90000
	v_lshl_add_u64 v[250:251], v[138:139], 0, s[100:101]
	global_load_dwordx4 v[234:237], v[250:251], off offset:16 nt
	global_load_dwordx4 v[238:241], v[250:251], off nt
	global_load_dwordx4 v[242:245], v[250:251], off offset:528 nt
	global_load_dwordx4 v[246:249], v[250:251], off offset:512 nt
	s_waitcnt vmcnt(8)
	v_mov_b64_e32 v[156:157], v[128:129]
	v_mov_b64_e32 v[158:159], v[130:131]
	v_mov_b64_e32 v[160:161], v[132:133]
	v_mov_b64_e32 v[162:163], v[134:135]
	v_pk_add_f32 v[74:75], v[74:75], v[158:159]
	v_pk_add_f32 v[78:79], v[78:79], v[162:163]
	v_pk_add_f32 v[76:77], v[76:77], v[160:161]
	v_mov_b64_e32 v[158:159], v[202:203]
	v_mov_b64_e32 v[160:161], v[204:205]
	v_mov_b64_e32 v[162:163], v[206:207]
	v_mov_b64_e32 v[164:165], v[208:209]
	v_pk_add_f32 v[72:73], v[72:73], v[156:157]
	v_mul_f32_e32 v153, v77, v77
	v_fmac_f32_e32 v153, v76, v76
	v_fmac_f32_e32 v153, v78, v78
	v_fmac_f32_e32 v153, v79, v79
	v_fmac_f32_e32 v153, v72, v72
	v_fmac_f32_e32 v153, v73, v73
	v_fmac_f32_e32 v153, v74, v74
	v_fmac_f32_e32 v153, v75, v75
	v_pk_add_f32 v[66:67], v[66:67], v[160:161]
	v_pk_add_f32 v[156:157], v[68:69], v[162:163]
	v_pk_add_f32 v[68:69], v[64:65], v[158:159]
	v_mul_f32_e32 v64, v157, v157
	v_pk_add_f32 v[70:71], v[70:71], v[164:165]
	v_fmac_f32_e32 v64, v156, v156
	v_fmac_f32_e32 v64, v70, v70
	v_fmac_f32_e32 v64, v71, v71
	v_fmac_f32_e32 v64, v68, v68
	v_fmac_f32_e32 v64, v69, v69
	v_fmac_f32_e32 v64, v66, v66
	v_fmac_f32_e32 v64, v67, v67
	v_add_f32_e32 v64, v153, v64
	ds_bpermute_b32 v65, v172, v64
	v_lshl_add_u64 v[158:159], v[166:167], 2, s[12:13]
	s_waitcnt lgkmcnt(0)
	v_add_f32_e32 v64, v64, v65
	ds_bpermute_b32 v65, v173, v64
	s_and_saveexec_b64 s[34:35], s[38:39]
	s_cbranch_execz .LBB0_798
	s_waitcnt lgkmcnt(0)
	v_add_f32_e32 v64, v64, v65
	global_atomic_add_f32 v[158:159], v64, off
.LBB0_798:
	s_or_b64 exec, exec, s[34:35]
	v_add_u32_e32 v162, 0x80, v152
	v_ashrrev_i32_e32 v163, 31, v162
	s_waitcnt lgkmcnt(0)
	v_lshlrev_b64 v[64:65], 12, v[162:163]
	v_lshl_add_u64 v[64:65], s[22:23], 0, v[64:65]
	v_lshl_add_u64 v[64:65], v[140:141], 2, v[64:65]
	s_mov_b64 s[100:101], 0xa0000
	v_lshl_add_u64 v[250:251], v[138:139], 0, s[100:101]
	global_load_dwordx4 v[128:131], v[250:251], off offset:16 nt
	global_load_dwordx4 v[132:135], v[250:251], off nt
	global_load_dwordx4 v[202:205], v[250:251], off offset:528 nt
	global_load_dwordx4 v[206:209], v[250:251], off offset:512 nt
	s_waitcnt vmcnt(8)
	v_mov_b64_e32 v[164:165], v[210:211]
	v_mov_b64_e32 v[166:167], v[212:213]
	v_mov_b64_e32 v[174:175], v[214:215]
	v_mov_b64_e32 v[176:177], v[216:217]
	v_pk_add_f32 v[58:59], v[58:59], v[166:167]
	v_pk_add_f32 v[62:63], v[62:63], v[176:177]
	v_pk_add_f32 v[60:61], v[60:61], v[174:175]
	v_pk_add_f32 v[56:57], v[56:57], v[164:165]
	v_mov_b64_e32 v[164:165], v[218:219]
	v_mov_b64_e32 v[166:167], v[220:221]
	v_mov_b64_e32 v[174:175], v[230:231]
	v_mov_b64_e32 v[176:177], v[232:233]
	v_mul_f32_e32 v153, v61, v61
	v_fmac_f32_e32 v153, v60, v60
	v_fmac_f32_e32 v153, v62, v62
	v_fmac_f32_e32 v153, v63, v63
	v_fmac_f32_e32 v153, v56, v56
	v_fmac_f32_e32 v153, v57, v57
	v_fmac_f32_e32 v153, v58, v58
	v_fmac_f32_e32 v153, v59, v59
	v_pk_add_f32 v[50:51], v[50:51], v[166:167]
	v_pk_add_f32 v[160:161], v[52:53], v[174:175]
	v_pk_add_f32 v[52:53], v[48:49], v[164:165]
	v_mul_f32_e32 v48, v161, v161
	v_pk_add_f32 v[54:55], v[54:55], v[176:177]
	v_fmac_f32_e32 v48, v160, v160
	v_fmac_f32_e32 v48, v54, v54
	v_fmac_f32_e32 v48, v55, v55
	v_fmac_f32_e32 v48, v52, v52
	v_fmac_f32_e32 v48, v53, v53
	v_fmac_f32_e32 v48, v50, v50
	v_fmac_f32_e32 v48, v51, v51
	v_add_f32_e32 v48, v153, v48
	ds_bpermute_b32 v49, v172, v48
	s_waitcnt lgkmcnt(0)
	v_add_f32_e32 v48, v48, v49
	ds_bpermute_b32 v49, v173, v48
	s_and_saveexec_b64 s[34:35], s[38:39]
	s_cbranch_execz .LBB0_800
	v_lshl_add_u64 v[162:163], v[162:163], 2, s[12:13]
	s_waitcnt lgkmcnt(0)
	v_add_f32_e32 v48, v48, v49
	global_atomic_add_f32 v[162:163], v48, off
.LBB0_800:
	s_or_b64 exec, exec, s[34:35]
	v_add_u32_e32 v164, 0x90, v152
	v_ashrrev_i32_e32 v165, 31, v164
	s_waitcnt lgkmcnt(0)
	v_lshlrev_b64 v[48:49], 12, v[164:165]
	v_lshl_add_u64 v[48:49], s[22:23], 0, v[48:49]
	v_lshl_add_u64 v[48:49], v[140:141], 2, v[48:49]
	s_mov_b64 s[100:101], 0xb0000
	v_lshl_add_u64 v[250:251], v[138:139], 0, s[100:101]
	global_load_dwordx4 v[210:213], v[250:251], off offset:16 nt
	global_load_dwordx4 v[214:217], v[250:251], off nt
	global_load_dwordx4 v[218:221], v[250:251], off offset:528 nt
	global_load_dwordx4 v[230:233], v[250:251], off offset:512 nt
	s_waitcnt vmcnt(8)
	v_mov_b64_e32 v[174:175], v[234:235]
	v_mov_b64_e32 v[176:177], v[236:237]
	v_mov_b64_e32 v[178:179], v[238:239]
	v_mov_b64_e32 v[180:181], v[240:241]
	v_pk_add_f32 v[42:43], v[42:43], v[176:177]
	v_pk_add_f32 v[46:47], v[46:47], v[180:181]
	v_pk_add_f32 v[44:45], v[44:45], v[178:179]
	v_pk_add_f32 v[40:41], v[40:41], v[174:175]
	v_mov_b64_e32 v[174:175], v[242:243]
	v_mov_b64_e32 v[176:177], v[244:245]
	v_mov_b64_e32 v[178:179], v[246:247]
	v_mov_b64_e32 v[180:181], v[248:249]
	v_mul_f32_e32 v153, v45, v45
	v_fmac_f32_e32 v153, v44, v44
	v_fmac_f32_e32 v153, v46, v46
	v_fmac_f32_e32 v153, v47, v47
	v_fmac_f32_e32 v153, v40, v40
	v_fmac_f32_e32 v153, v41, v41
	v_fmac_f32_e32 v153, v42, v42
	v_fmac_f32_e32 v153, v43, v43
	v_pk_add_f32 v[34:35], v[34:35], v[176:177]
	v_pk_add_f32 v[162:163], v[36:37], v[178:179]
	v_pk_add_f32 v[36:37], v[32:33], v[174:175]
	v_mul_f32_e32 v32, v163, v163
	v_pk_add_f32 v[38:39], v[38:39], v[180:181]
	v_fmac_f32_e32 v32, v162, v162
	v_fmac_f32_e32 v32, v38, v38
	v_fmac_f32_e32 v32, v39, v39
	v_fmac_f32_e32 v32, v36, v36
	v_fmac_f32_e32 v32, v37, v37
	v_fmac_f32_e32 v32, v34, v34
	v_fmac_f32_e32 v32, v35, v35
	v_add_f32_e32 v32, v153, v32
	ds_bpermute_b32 v33, v172, v32
	s_waitcnt lgkmcnt(0)
	v_add_f32_e32 v32, v32, v33
	ds_bpermute_b32 v33, v173, v32
	s_and_saveexec_b64 s[34:35], s[38:39]
	s_cbranch_execz .LBB0_802
	v_lshl_add_u64 v[164:165], v[164:165], 2, s[12:13]
	s_waitcnt lgkmcnt(0)
	v_add_f32_e32 v32, v32, v33
	global_atomic_add_f32 v[164:165], v32, off
.LBB0_802:
	s_or_b64 exec, exec, s[34:35]
	v_add_u32_e32 v166, 0xa0, v152
	v_ashrrev_i32_e32 v167, 31, v166
	s_waitcnt lgkmcnt(0)
	v_lshlrev_b64 v[32:33], 12, v[166:167]
	v_lshl_add_u64 v[32:33], s[22:23], 0, v[32:33]
	v_lshl_add_u64 v[32:33], v[140:141], 2, v[32:33]
	s_waitcnt vmcnt(4)
	v_mov_b64_e32 v[174:175], v[128:129]
	v_mov_b64_e32 v[176:177], v[130:131]
	v_mov_b64_e32 v[178:179], v[132:133]
	v_mov_b64_e32 v[180:181], v[134:135]
	v_pk_add_f32 v[26:27], v[26:27], v[176:177]
	v_pk_add_f32 v[30:31], v[30:31], v[180:181]
	v_pk_add_f32 v[28:29], v[28:29], v[178:179]
	v_pk_add_f32 v[24:25], v[24:25], v[174:175]
	v_mov_b64_e32 v[174:175], v[202:203]
	v_mov_b64_e32 v[176:177], v[204:205]
	v_mov_b64_e32 v[178:179], v[206:207]
	v_mov_b64_e32 v[180:181], v[208:209]
	v_mul_f32_e32 v153, v29, v29
	v_fmac_f32_e32 v153, v28, v28
	v_fmac_f32_e32 v153, v30, v30
	v_fmac_f32_e32 v153, v31, v31
	v_fmac_f32_e32 v153, v24, v24
	v_fmac_f32_e32 v153, v25, v25
	v_fmac_f32_e32 v153, v26, v26
	v_fmac_f32_e32 v153, v27, v27
	v_pk_add_f32 v[18:19], v[18:19], v[176:177]
	v_pk_add_f32 v[164:165], v[20:21], v[178:179]
	v_pk_add_f32 v[20:21], v[16:17], v[174:175]
	v_mul_f32_e32 v16, v165, v165
	v_pk_add_f32 v[22:23], v[22:23], v[180:181]
	v_fmac_f32_e32 v16, v164, v164
	v_fmac_f32_e32 v16, v22, v22
	v_fmac_f32_e32 v16, v23, v23
	v_fmac_f32_e32 v16, v20, v20
	v_fmac_f32_e32 v16, v21, v21
	v_fmac_f32_e32 v16, v18, v18
	v_fmac_f32_e32 v16, v19, v19
	v_add_f32_e32 v16, v153, v16
	ds_bpermute_b32 v17, v172, v16
	s_waitcnt lgkmcnt(0)
	v_add_f32_e32 v16, v16, v17
	ds_bpermute_b32 v17, v173, v16
	s_and_saveexec_b64 s[34:35], s[38:39]
	s_cbranch_execz .LBB0_804
	v_lshl_add_u64 v[166:167], v[166:167], 2, s[12:13]
	s_waitcnt lgkmcnt(0)
	v_add_f32_e32 v16, v16, v17
	global_atomic_add_f32 v[166:167], v16, off
.LBB0_804:
	s_or_b64 exec, exec, s[34:35]
	v_add_u32_e32 v152, 0xb0, v152
	v_ashrrev_i32_e32 v153, 31, v152
	s_waitcnt lgkmcnt(0)
	v_lshlrev_b64 v[16:17], 12, v[152:153]
	v_lshl_add_u64 v[16:17], s[22:23], 0, v[16:17]
	v_lshl_add_u64 v[16:17], v[140:141], 2, v[16:17]
	s_waitcnt vmcnt(0)
	v_mov_b64_e32 v[174:175], v[210:211]
	v_mov_b64_e32 v[176:177], v[212:213]
	v_mov_b64_e32 v[178:179], v[214:215]
	v_mov_b64_e32 v[180:181], v[216:217]
	v_pk_add_f32 v[10:11], v[10:11], v[176:177]
	v_pk_add_f32 v[14:15], v[14:15], v[180:181]
	v_pk_add_f32 v[12:13], v[12:13], v[178:179]
	v_pk_add_f32 v[8:9], v[8:9], v[174:175]
	v_mov_b64_e32 v[174:175], v[218:219]
	v_mov_b64_e32 v[176:177], v[220:221]
	v_mov_b64_e32 v[178:179], v[230:231]
	v_mov_b64_e32 v[180:181], v[232:233]
	v_mul_f32_e32 v166, v13, v13
	v_fmac_f32_e32 v166, v12, v12
	v_fmac_f32_e32 v166, v14, v14
	v_fmac_f32_e32 v166, v15, v15
	v_fmac_f32_e32 v166, v8, v8
	v_fmac_f32_e32 v166, v9, v9
	v_fmac_f32_e32 v166, v10, v10
	v_fmac_f32_e32 v166, v11, v11
	v_pk_add_f32 v[0:1], v[0:1], v[174:175]
	v_pk_add_f32 v[4:5], v[4:5], v[178:179]
	v_pk_add_f32 v[6:7], v[6:7], v[180:181]
	v_mul_f32_e32 v167, v5, v5
	v_fmac_f32_e32 v167, v4, v4
	v_fmac_f32_e32 v167, v6, v6
	v_fmac_f32_e32 v167, v7, v7
	v_fmac_f32_e32 v167, v0, v0
	v_pk_add_f32 v[2:3], v[2:3], v[176:177]
	v_fmac_f32_e32 v167, v1, v1
	v_fmac_f32_e32 v167, v2, v2
	v_fmac_f32_e32 v167, v3, v3
	v_add_f32_e32 v166, v166, v167
	ds_bpermute_b32 v167, v172, v166
	s_waitcnt lgkmcnt(0)
	v_add_f32_e32 v166, v166, v167
	ds_bpermute_b32 v167, v173, v166
	s_and_saveexec_b64 s[34:35], s[38:39]
	s_cbranch_execz .LBB0_806
	v_lshl_add_u64 v[152:153], v[152:153], 2, s[12:13]
	s_waitcnt lgkmcnt(0)
	v_add_f32_e32 v166, v166, v167
	global_atomic_add_f32 v[152:153], v166, off
